# attention: in-place score scaling in the P.V gaps packed two per v_pk_fma_f32 (bit-identical fma per half)
# speedup vs baseline: 1.0260x; 1.0012x over previous
; #define SBAR() __builtin_amdgcn_sched_barrier(0)
; __device__ __forceinline__ void finishSM(f32x16& p0, f32x16& p1, float alpha, float& l_reg, bf16x8& pa0, bf16x8& pa1, bf16x8& pa2, bf16x8& pa3) {
; #pragma unroll
;     for (int r = 0; r < 16; ++r) p1[r] = __builtin_amdgcn_exp2f(p1[r]);
;     float ps = 0;
; #pragma unroll
;     for (int r = 0; r < 16; ++r) ps += p0[r];
; #pragma unroll
;     for (int r = 0; r < 16; ++r) ps += p1[r];
;     { auto rr = __builtin_amdgcn_permlane32_swap(__float_as_uint(ps), __float_as_uint(ps), false, false);
;       ps = __uint_as_float(rr[0]) + __uint_as_float(rr[1]); }
;     l_reg = l_reg * alpha + ps;
;     ...
;     PK4(p0, 0, pa0); PK4(p0, 8, pa1); PK4(p1, 0, pa2); PK4(p1, 8, pa3);
;     ...
; }
; __device__ __forceinline__ void attn_unit(const bf16_t* Qb, const bf16_t* Kh, const bf16_t* Vh, bf16_t* Ob, float* scr, int seq, float lam, float onemli, const float* subg, char* lds) {
;     ...
;         for (int j = 1; j + 1 < NT; j += 2) {
;             SBAR(); qkt(pB0, pB1, K_lds + SHM_K, qr, r32, hi, comp);
;             finishSM(pA0, pA1, alA, l_reg, pa0, pa1, pa2, pa3); SBAR();
;             SLOAD(SO, (j + 1) * KVBLK); SBAR();
;             pv_d0(o, vb0, pa0, pa1, pa2, pa3); partialSM(pB0, pB1, m_reg, mnB, alB);
.LBB0_262:
	ds_read_b128 v[64:67], v170 offset:49152
	ds_read_b128 v[68:71], v170 offset:57344
	v_add_f32_e32 v177, 0, v240
	v_add_f32_e32 v177, v241, v177
	v_add_f32_e32 v177, v242, v177
	s_waitcnt lgkmcnt(1)
	v_mfma_f32_32x32x16_bf16 v[80:95], v[64:67], v[110:113], 0
	v_add_f32_e32 v177, v243, v177
	v_add_f32_e32 v177, v244, v177
	ds_read_b128 v[178:181], v171 offset:49152
	ds_read_b128 v[220:223], v171 offset:57344
	v_add_f32_e32 v177, v245, v177
	v_add_f32_e32 v177, v246, v177
	v_add_f32_e32 v177, v247, v177
	v_add_f32_e32 v177, v248, v177
	s_waitcnt lgkmcnt(2)
	v_mfma_f32_32x32x16_bf16 v[64:79], v[68:71], v[110:113], 0
	v_add_f32_e32 v177, v249, v177
	v_add_f32_e32 v177, v250, v177
	v_add_f32_e32 v177, v251, v177
	v_exp_f32_e32 v128, v128
	v_add_f32_e32 v177, v206, v177
	v_exp_f32_e32 v129, v129
	v_add_f32_e32 v177, v207, v177
	s_waitcnt lgkmcnt(1)
	v_mfma_f32_32x32x16_bf16 v[80:95], v[178:181], v[106:109], v[80:95]
	v_exp_f32_e32 v126, v126
	v_add_f32_e32 v177, v208, v177
	v_exp_f32_e32 v127, v127
	v_add_f32_e32 v177, v209, v177
	v_exp_f32_e32 v122, v122
	v_add_f32_e32 v177, v128, v177
	v_exp_f32_e32 v123, v123
	s_waitcnt lgkmcnt(0)
	v_mfma_f32_32x32x16_bf16 v[64:79], v[220:223], v[106:109], v[64:79]
	ds_read_b128 v[178:181], v173 offset:49152
	ds_read_b128 v[220:223], v173 offset:57344
	v_add_f32_e32 v177, v129, v177
	v_exp_f32_e32 v118, v118
	v_add_f32_e32 v177, v126, v177
	v_exp_f32_e32 v119, v119
	v_add_f32_e32 v177, v127, v177
	v_exp_f32_e32 v116, v116
	s_waitcnt lgkmcnt(1)
	v_mfma_f32_32x32x16_bf16 v[80:95], v[178:181], v[102:105], v[80:95]
	v_add_f32_e32 v177, v122, v177
	v_exp_f32_e32 v117, v117
	v_add_f32_e32 v177, v123, v177
	v_exp_f32_e32 v124, v124
	v_add_f32_e32 v177, v118, v177
	v_exp_f32_e32 v125, v125
	v_add_f32_e32 v177, v119, v177
	s_waitcnt lgkmcnt(0)
	v_mfma_f32_32x32x16_bf16 v[64:79], v[220:223], v[102:105], v[64:79]
	ds_read_b128 v[178:181], v172 offset:49152
	ds_read_b128 v[220:223], v172 offset:57344
	v_exp_f32_e32 v120, v120
	v_add_f32_e32 v177, v116, v177
	v_exp_f32_e32 v121, v121
	v_add_f32_e32 v177, v117, v177
	v_exp_f32_e32 v114, v114
	v_add_f32_e32 v177, v124, v177
	s_waitcnt lgkmcnt(1)
	v_mfma_f32_32x32x16_bf16 v[80:95], v[178:181], v[98:101], v[80:95]
	v_exp_f32_e32 v115, v115
	v_add_f32_e32 v177, v125, v177
	v_add_f32_e32 v177, v120, v177
	v_add_f32_e32 v177, v121, v177
	v_add_f32_e32 v177, v114, v177
	v_add_f32_e32 v177, v115, v177
	v_mov_b32_e32 v178, v177
	s_waitcnt lgkmcnt(0)
	v_mfma_f32_32x32x16_bf16 v[64:79], v[220:223], v[98:101], v[64:79]
	v_cvt_pk_bf16_f32 v212, v240, v241
	v_cvt_pk_bf16_f32 v213, v242, v243
	v_cvt_pk_bf16_f32 v214, v244, v245
	v_cvt_pk_bf16_f32 v215, v246, v247
	v_cvt_pk_bf16_f32 v180, v248, v249
	v_cvt_pk_bf16_f32 v181, v250, v251
	v_cvt_pk_bf16_f32 v182, v206, v207
	v_permlane32_swap_b32_e32 v177, v178
	v_cvt_pk_bf16_f32 v183, v208, v209
	v_permlane32_swap_b32_e32 v180, v182
	v_cvt_pk_bf16_f32 v184, v128, v129
	v_cvt_pk_bf16_f32 v185, v126, v127
	v_cvt_pk_bf16_f32 v186, v122, v123
	v_cvt_pk_bf16_f32 v187, v118, v119
	v_cvt_pk_bf16_f32 v216, v116, v117
	v_cvt_pk_bf16_f32 v217, v124, v125
	v_cvt_pk_bf16_f32 v218, v120, v121
	v_cvt_pk_bf16_f32 v219, v114, v115
	v_permlane32_swap_b32_e32 v212, v214
	v_permlane32_swap_b32_e32 v213, v215
	v_permlane32_swap_b32_e32 v181, v183
	v_permlane32_swap_b32_e32 v184, v186
	v_permlane32_swap_b32_e32 v185, v187
	v_permlane32_swap_b32_e32 v216, v218
	v_permlane32_swap_b32_e32 v217, v219
	v_add_u32_e32 v122, 0x10000, v176
	global_load_dwordx4 v[240:243], v176, s[58:59]
	global_load_dwordx4 v[244:247], v176, s[28:29]
	global_load_dwordx4 v[206:209], v122, s[58:59]
	s_nop 0
	global_load_dwordx4 v[248:251], v122, s[28:29]
	ds_read_b64_tr_b16 v[220:221], v160 offset:0
	ds_read_b64_tr_b16 v[222:223], v160 offset:0x800
	ds_read_b64_tr_b16 v[224:225], v160 offset:0x1000
	ds_read_b64_tr_b16 v[226:227], v160 offset:0x1800
	ds_read_b64_tr_b16 v[228:229], v160 offset:0x2000
	ds_read_b64_tr_b16 v[230:231], v160 offset:0x2800
	ds_read_b64_tr_b16 v[232:233], v160 offset:0x3000
	ds_read_b64_tr_b16 v[234:235], v160 offset:0x3800
	s_waitcnt lgkmcnt(0)
	s_nop 0
	v_mfma_f32_32x32x16_bf16 v[48:63], v[212:215], v[220:223], v[48:63]
	ds_read_b64_tr_b16 v[220:221], v160 offset:0x200
	ds_read_b64_tr_b16 v[222:223], v160 offset:0xa00
	v_max_f32_e32 v179, v81, v81
	v_max_f32_e32 v255, v80, v80
	v_max_f32_e32 v179, v255, v179
	v_max3_f32 v179, v179, v82, v83
	v_max3_f32 v179, v179, v84, v85
	v_mfma_f32_32x32x16_bf16 v[48:63], v[180:183], v[224:227], v[48:63]
	ds_read_b64_tr_b16 v[224:225], v160 offset:0x1200
	ds_read_b64_tr_b16 v[226:227], v160 offset:0x1a00
	v_max3_f32 v179, v179, v86, v87
	v_max3_f32 v179, v179, v88, v89
	v_max3_f32 v179, v179, v90, v91
	v_max3_f32 v179, v179, v92, v93
	v_max3_f32 v179, v179, v94, v95
	v_mfma_f32_32x32x16_bf16 v[48:63], v[184:187], v[228:231], v[48:63]
	ds_read_b64_tr_b16 v[228:229], v160 offset:0x2200
	ds_read_b64_tr_b16 v[230:231], v160 offset:0x2a00
	v_max3_f32 v179, v179, v64, v65
	v_max3_f32 v179, v179, v66, v67
	v_max3_f32 v179, v179, v68, v69
	v_max3_f32 v179, v179, v70, v71
	v_max3_f32 v179, v179, v72, v73
	v_mfma_f32_32x32x16_bf16 v[48:63], v[216:219], v[232:235], v[48:63]
	ds_read_b64_tr_b16 v[232:233], v160 offset:0x3200
	ds_read_b64_tr_b16 v[234:235], v160 offset:0x3a00
	v_max3_f32 v179, v179, v74, v75
	v_max3_f32 v179, v179, v76, v77
	v_max3_f32 v179, v179, v78, v79
	v_mov_b32_e32 v255, v179
	s_nop 1
	v_permlane32_swap_b32_e32 v179, v255
	s_waitcnt lgkmcnt(0)
; #define SBAR() __builtin_amdgcn_sched_barrier(0)
; #define SWRITE(b, i) do { *(bf16x8*)(V_lds + (b) * SHM_V + vst0) = sr_[i].vs0;          \
;     *(bf16x8*)(V_lds + (b) * SHM_V + vst1) = sr_[i].vs1; int kc = sc * 2;               \
;     *(bf16x8*)(K_lds + (b) * SHM_K + KSWZ(sr, kc)) = sr_[i].ks0;                       \
;     *(bf16x8*)(K_lds + (b) * SHM_K + KSWZ(32 + sr, kc)) = sr_[i].ks1; } while (0)
; #define SWAIT() asm volatile("s_waitcnt vmcnt(0)" ::: "memory")
; #define RESC(a) do { if (__any((a) < 1.f)) { if (hi == 0) al_l[r32] = (a); asm volatile("s_waitcnt lgkmcnt(0)" ::: "memory"); \
;     _Pragma("unroll") for (int d = 0; d < 4; ++d) _Pragma("unroll") for (int r = 0; r < 16; ++r) o[d][r] *= al_l[crow(r, hi)]; } } while (0)
; __device__ __forceinline__ void partialSM(f32x16& p0, f32x16& p1, float& m_reg, float& mn, float& alpha) {
;     constexpr float C = SCALE * 1.4426950408889634f;
;     float pmax = p0[0];
; #pragma unroll
;     for (int r = 1; r < 16; ++r) pmax = fmaxf(pmax, p0[r]);
; #pragma unroll
;     for (int r = 0; r < 16; ++r) pmax = fmaxf(pmax, p1[r]);
;     { auto rr = __builtin_amdgcn_permlane32_swap(__float_as_uint(pmax), __float_as_uint(pmax), false, false);
;       pmax = fmaxf(__uint_as_float(rr[0]), __uint_as_float(rr[1])); }
;     if (__builtin_expect(__all(pmax - m_reg <= THR / SCALE), 1)) { mn = m_reg; alpha = 1.f; }
;     else { mn = fmaxf(m_reg, pmax); alpha = __builtin_amdgcn_exp2f((m_reg - mn) * C); m_reg = mn; }
;     const float mnC = -mn * C;
; #pragma unroll
;     for (int r = 0; r < 16; ++r) p0[r] = fmaf(p0[r], C, mnC);
; #pragma unroll
;     for (int r = 0; r < 16; ++r) p1[r] = fmaf(p1[r], C, mnC);
; #pragma unroll
;     for (int r = 0; r < 16; ++r) p0[r] = __builtin_amdgcn_exp2f(p0[r]);
; }
; __device__ __forceinline__ void attn_unit(const bf16_t* Qb, const bf16_t* Kh, const bf16_t* Vh, bf16_t* Ob, float* scr, int seq, float lam, float onemli, const float* subg, char* lds) {
;     ...
;             SLOAD(SO, (j + 1) * KVBLK); SBAR();
;             pv_d0(o, vb0, pa0, pa1, pa2, pa3); partialSM(pB0, pB1, m_reg, mnB, alB);
;             __syncthreads(); SWAIT(); SWRITE(0, SE);
;             RESC(alB); __syncthreads();
	v_mfma_f32_32x32x16_bf16 v[32:47], v[212:215], v[220:223], v[32:47]
	ds_read_b64_tr_b16 v[220:221], v160 offset:0x400
	ds_read_b64_tr_b16 v[222:223], v160 offset:0xc00
	v_max_f32_e32 v255, v255, v255
	v_max_f32_e32 v179, v179, v179
	v_max_f32_e32 v179, v179, v255
	v_sub_f32_e32 v255, v179, v175
	v_cmp_ge_f32_e32 vcc, s65, v255
	v_mfma_f32_32x32x16_bf16 v[32:47], v[180:183], v[224:227], v[32:47]
	ds_read_b64_tr_b16 v[224:225], v160 offset:0x1400
	ds_read_b64_tr_b16 v[226:227], v160 offset:0x1c00
	v_max_f32_e32 v255, v175, v175
	v_max_f32_e32 v179, v255, v179
	v_sub_f32_e32 v255, v175, v179
	v_mul_f32_e32 v255, 0x3e38aa3b, v255
	v_exp_f32_e32 v255, v255
	v_mfma_f32_32x32x16_bf16 v[32:47], v[184:187], v[228:231], v[32:47]
	ds_read_b64_tr_b16 v[228:229], v160 offset:0x2400
	ds_read_b64_tr_b16 v[230:231], v160 offset:0x2c00
	s_cmp_eq_u64 vcc, exec
	s_cselect_b64 s[8:9], -1, 0
	v_cndmask_b32_e64 v255, v255, 1.0, s[8:9]
	v_cndmask_b32_e64 v175, v179, v175, s[8:9]
	v_mul_f32_e32 v179, 0xbe38aa3b, v175
	v_mfma_f32_32x32x16_bf16 v[32:47], v[216:219], v[232:235], v[32:47]
	ds_read_b64_tr_b16 v[232:233], v160 offset:0x3400
	ds_read_b64_tr_b16 v[234:235], v160 offset:0x3c00
	v_pk_fma_f32 v[80:81], v[80:81], s[72:73], v[178:179] op_sel:[0,0,1] op_sel_hi:[1,0,1]
	v_pk_fma_f32 v[82:83], v[82:83], s[72:73], v[178:179] op_sel:[0,0,1] op_sel_hi:[1,0,1]
	v_pk_fma_f32 v[84:85], v[84:85], s[72:73], v[178:179] op_sel:[0,0,1] op_sel_hi:[1,0,1]
	v_pk_fma_f32 v[86:87], v[86:87], s[72:73], v[178:179] op_sel:[0,0,1] op_sel_hi:[1,0,1]
	v_pk_fma_f32 v[88:89], v[88:89], s[72:73], v[178:179] op_sel:[0,0,1] op_sel_hi:[1,0,1]
	s_waitcnt lgkmcnt(0)
	v_mfma_f32_32x32x16_bf16 v[16:31], v[212:215], v[220:223], v[16:31]
	ds_read_b64_tr_b16 v[220:221], v160 offset:0x600
	ds_read_b64_tr_b16 v[222:223], v160 offset:0xe00
	v_pk_fma_f32 v[90:91], v[90:91], s[72:73], v[178:179] op_sel:[0,0,1] op_sel_hi:[1,0,1]
	v_pk_fma_f32 v[92:93], v[92:93], s[72:73], v[178:179] op_sel:[0,0,1] op_sel_hi:[1,0,1]
	v_pk_fma_f32 v[94:95], v[94:95], s[72:73], v[178:179] op_sel:[0,0,1] op_sel_hi:[1,0,1]
	v_exp_f32_e32 v127, v80
	v_mfma_f32_32x32x16_bf16 v[16:31], v[180:183], v[224:227], v[16:31]
	ds_read_b64_tr_b16 v[224:225], v160 offset:0x1600
	ds_read_b64_tr_b16 v[226:227], v160 offset:0x1e00
	v_exp_f32_e32 v129, v81
	v_exp_f32_e32 v125, v82
	v_exp_f32_e32 v128, v83
	v_mfma_f32_32x32x16_bf16 v[16:31], v[184:187], v[228:231], v[16:31]
	ds_read_b64_tr_b16 v[228:229], v160 offset:0x2600
	ds_read_b64_tr_b16 v[230:231], v160 offset:0x2e00
	v_exp_f32_e32 v123, v84
	v_exp_f32_e32 v126, v85
	v_exp_f32_e32 v122, v86
	v_mfma_f32_32x32x16_bf16 v[16:31], v[216:219], v[232:235], v[16:31]
	ds_read_b64_tr_b16 v[232:233], v160 offset:0x3600
	ds_read_b64_tr_b16 v[234:235], v160 offset:0x3e00
	v_exp_f32_e32 v124, v87
	v_exp_f32_e32 v119, v88
	v_exp_f32_e32 v121, v89
	s_waitcnt lgkmcnt(0)
	v_mfma_f32_32x32x16_bf16 v[0:15], v[212:215], v[220:223], v[0:15]
	s_barrier
	s_waitcnt vmcnt(0)
	s_waitcnt vmcnt(3)
	ds_write_b128 v163, v[240:243]
	s_waitcnt vmcnt(1)
	ds_write_b128 v164, v[206:209]
	ds_write_b128 v161, v[244:247] offset:32768
	s_waitcnt vmcnt(0)
	ds_write_b128 v162, v[248:251] offset:32768
	v_exp_f32_e32 v117, v90
	v_exp_f32_e32 v120, v91
	v_exp_f32_e32 v115, v92
	v_mfma_f32_32x32x16_bf16 v[0:15], v[180:183], v[224:227], v[0:15]
	v_exp_f32_e32 v118, v93
	v_exp_f32_e32 v114, v94
	v_exp_f32_e32 v116, v95
	v_mfma_f32_32x32x16_bf16 v[0:15], v[184:187], v[228:231], v[0:15]
	v_mfma_f32_32x32x16_bf16 v[0:15], v[216:219], v[232:235], v[0:15]
	v_mov_b32_e32 v180, v255
	v_cmp_gt_f32_e32 vcc, 1.0, v180
	s_cbranch_vccz .LBB0_266
	s_and_saveexec_b64 s[2:3], s[6:7]
	ds_write_b32 v157, v180 offset:128
	s_or_b64 exec, exec, s[2:3]
	s_waitcnt lgkmcnt(0)
	ds_read_b128 v[240:243], v158 offset:224
	ds_read_b128 v[244:247], v158 offset:192
	ds_read_b128 v[248:251], v158 offset:160
	ds_read_b128 v[206:209], v158 offset:128
	s_waitcnt lgkmcnt(3)
	v_pk_mul_f32 v[62:63], v[62:63], v[242:243]
	s_waitcnt lgkmcnt(2)
	v_pk_mul_f32 v[58:59], v[58:59], v[246:247]
	s_waitcnt lgkmcnt(1)
	v_pk_mul_f32 v[54:55], v[54:55], v[250:251]
	s_waitcnt lgkmcnt(0)
	v_pk_mul_f32 v[50:51], v[50:51], v[208:209]
	v_pk_mul_f32 v[60:61], v[60:61], v[240:241]
	v_pk_mul_f32 v[56:57], v[56:57], v[244:245]
	v_pk_mul_f32 v[52:53], v[52:53], v[248:249]
	v_pk_mul_f32 v[48:49], v[48:49], v[206:207]
	v_pk_mul_f32 v[46:47], v[46:47], v[242:243]
	v_pk_mul_f32 v[42:43], v[42:43], v[246:247]
	v_pk_mul_f32 v[38:39], v[38:39], v[250:251]
	v_pk_mul_f32 v[34:35], v[34:35], v[208:209]
	v_pk_mul_f32 v[44:45], v[44:45], v[240:241]
	v_pk_mul_f32 v[40:41], v[40:41], v[244:245]
	v_pk_mul_f32 v[36:37], v[36:37], v[248:249]
	v_pk_mul_f32 v[32:33], v[32:33], v[206:207]
	v_pk_mul_f32 v[30:31], v[30:31], v[242:243]
	v_pk_mul_f32 v[26:27], v[26:27], v[246:247]
	v_pk_mul_f32 v[22:23], v[22:23], v[250:251]
	v_pk_mul_f32 v[18:19], v[18:19], v[208:209]
	v_pk_mul_f32 v[28:29], v[28:29], v[240:241]
	v_pk_mul_f32 v[24:25], v[24:25], v[244:245]
	v_pk_mul_f32 v[20:21], v[20:21], v[248:249]
	v_pk_mul_f32 v[16:17], v[16:17], v[206:207]
	v_pk_mul_f32 v[14:15], v[14:15], v[242:243]
	v_pk_mul_f32 v[10:11], v[10:11], v[246:247]
	v_pk_mul_f32 v[6:7], v[6:7], v[250:251]
	v_pk_mul_f32 v[2:3], v[2:3], v[208:209]
	v_pk_mul_f32 v[12:13], v[12:13], v[240:241]
	v_pk_mul_f32 v[8:9], v[8:9], v[244:245]
	v_pk_mul_f32 v[4:5], v[4:5], v[248:249]
	v_pk_mul_f32 v[0:1], v[0:1], v[206:207]
; #define SBAR() __builtin_amdgcn_sched_barrier(0)
; #define RESC(a) do { if (__any((a) < 1.f)) { if (hi == 0) al_l[r32] = (a); asm volatile("s_waitcnt lgkmcnt(0)" ::: "memory"); \
;     _Pragma("unroll") for (int d = 0; d < 4; ++d) _Pragma("unroll") for (int r = 0; r < 16; ++r) o[d][r] *= al_l[crow(r, hi)]; } } while (0)
; __device__ __forceinline__ void finishSM(f32x16& p0, f32x16& p1, float alpha, float& l_reg, bf16x8& pa0, bf16x8& pa1, bf16x8& pa2, bf16x8& pa3) {
; #pragma unroll
;     for (int r = 0; r < 16; ++r) p1[r] = __builtin_amdgcn_exp2f(p1[r]);
;     float ps = 0;
; #pragma unroll
;     for (int r = 0; r < 16; ++r) ps += p0[r];
; #pragma unroll
;     for (int r = 0; r < 16; ++r) ps += p1[r];
;     { auto rr = __builtin_amdgcn_permlane32_swap(__float_as_uint(ps), __float_as_uint(ps), false, false);
;       ps = __uint_as_float(rr[0]) + __uint_as_float(rr[1]); }
;     l_reg = l_reg * alpha + ps;
;     ...
;     PK4(p0, 0, pa0); PK4(p0, 8, pa1); PK4(p1, 0, pa2); PK4(p1, 8, pa3);
;     ...
; }
; __device__ __forceinline__ void attn_unit(const bf16_t* Qb, const bf16_t* Kh, const bf16_t* Vh, bf16_t* Ob, float* scr, int seq, float lam, float onemli, const float* subg, char* lds) {
;     ...
;             RESC(alB); __syncthreads();
;             SBAR(); qkt(pA0, pA1, K_lds, qr, r32, hi, comp);
;             finishSM(pB0, pB1, alB, l_reg, pa0, pa1, pa2, pa3); SBAR();
;             SLOAD(SE, (j + 2) * KVBLK); SBAR();
;             pv_d0(o, vb0 + (int)SHM_V, pa0, pa1, pa2, pa3); partialSM(pA0, pA1, m_reg, mnA, alA);
.LBB0_266:
	v_fmamk_f32 v189, v64, 0x3e38aa3b, v179
	v_fmamk_f32 v211, v65, 0x3e38aa3b, v179
	v_fmamk_f32 v212, v66, 0x3e38aa3b, v179
	v_fmamk_f32 v213, v67, 0x3e38aa3b, v179
	v_fmamk_f32 v214, v68, 0x3e38aa3b, v179
	v_fmamk_f32 v182, v69, 0x3e38aa3b, v179
	v_fmamk_f32 v183, v70, 0x3e38aa3b, v179
	v_fmamk_f32 v184, v71, 0x3e38aa3b, v179
	v_fmamk_f32 v185, v72, 0x3e38aa3b, v179
	v_fmamk_f32 v186, v73, 0x3e38aa3b, v179
	v_fmamk_f32 v187, v74, 0x3e38aa3b, v179
	v_fmamk_f32 v188, v75, 0x3e38aa3b, v179
	v_fmamk_f32 v181, v76, 0x3e38aa3b, v179
	v_fmamk_f32 v215, v77, 0x3e38aa3b, v179
	v_fmamk_f32 v216, v78, 0x3e38aa3b, v179
	v_fmac_f32_e32 v179, 0x3e38aa3b, v79
	s_waitcnt lgkmcnt(0)
	s_barrier
	ds_read_b128 v[64:67], v170 offset:32768
	ds_read_b128 v[68:71], v170 offset:40960
	v_exp_f32_e32 v203, v181
	v_add_f32_e32 v181, 0, v127
	v_add_f32_e32 v181, v129, v181
	s_waitcnt lgkmcnt(1)
	v_mfma_f32_32x32x16_bf16 v[80:95], v[64:67], v[110:113], 0
	v_add_f32_e32 v181, v125, v181
	v_add_f32_e32 v181, v128, v181
	v_add_f32_e32 v181, v123, v181
	ds_read_b128 v[218:221], v171 offset:32768
	ds_read_b128 v[222:225], v171 offset:40960
	v_add_f32_e32 v181, v126, v181
	v_add_f32_e32 v181, v122, v181
	v_add_f32_e32 v181, v124, v181
	s_waitcnt lgkmcnt(2)
	v_mfma_f32_32x32x16_bf16 v[64:79], v[68:71], v[110:113], 0
	v_add_f32_e32 v181, v119, v181
	v_add_f32_e32 v181, v121, v181
	v_add_f32_e32 v181, v117, v181
	v_add_f32_e32 v181, v120, v181
	v_exp_f32_e32 v189, v189
	v_add_f32_e32 v181, v115, v181
	v_exp_f32_e32 v190, v211
	s_waitcnt lgkmcnt(1)
	v_mfma_f32_32x32x16_bf16 v[80:95], v[218:221], v[106:109], v[80:95]
	v_add_f32_e32 v181, v118, v181
	v_exp_f32_e32 v191, v212
	v_add_f32_e32 v181, v114, v181
	v_exp_f32_e32 v192, v213
	v_add_f32_e32 v181, v116, v181
	v_exp_f32_e32 v193, v214
	v_add_f32_e32 v181, v189, v181
	s_waitcnt lgkmcnt(0)
	v_mfma_f32_32x32x16_bf16 v[64:79], v[222:225], v[106:109], v[64:79]
	ds_read_b128 v[218:221], v173 offset:32768
	ds_read_b128 v[222:225], v173 offset:40960
	v_exp_f32_e32 v194, v182
	v_add_f32_e32 v181, v190, v181
	v_exp_f32_e32 v183, v183
	v_add_f32_e32 v181, v191, v181
	v_exp_f32_e32 v195, v184
	v_add_f32_e32 v181, v192, v181
	s_waitcnt lgkmcnt(1)
	v_mfma_f32_32x32x16_bf16 v[80:95], v[218:221], v[102:105], v[80:95]
	v_exp_f32_e32 v200, v185
	v_add_f32_e32 v181, v193, v181
	v_exp_f32_e32 v201, v186
	v_add_f32_e32 v181, v194, v181
	v_exp_f32_e32 v202, v187
	v_add_f32_e32 v181, v183, v181
	v_exp_f32_e32 v188, v188
	s_waitcnt lgkmcnt(0)
	v_mfma_f32_32x32x16_bf16 v[64:79], v[222:225], v[102:105], v[64:79]
	ds_read_b128 v[218:221], v172 offset:32768
	ds_read_b128 v[222:225], v172 offset:40960
	v_add_f32_e32 v181, v195, v181
	v_add_f32_e32 v181, v200, v181
	v_exp_f32_e32 v204, v215
	v_add_f32_e32 v181, v201, v181
	v_exp_f32_e32 v205, v216
	v_add_f32_e32 v181, v202, v181
	s_waitcnt lgkmcnt(1)
	v_mfma_f32_32x32x16_bf16 v[80:95], v[218:221], v[98:101], v[80:95]
	v_exp_f32_e32 v179, v179
	v_add_f32_e32 v181, v188, v181
	v_add_f32_e32 v181, v203, v181
	v_add_f32_e32 v181, v204, v181
	v_add_f32_e32 v181, v205, v181
	v_add_f32_e32 v181, v179, v181
	v_mov_b32_e32 v182, v181
	s_waitcnt lgkmcnt(0)
	v_mfma_f32_32x32x16_bf16 v[64:79], v[222:225], v[98:101], v[64:79]
	v_permlane32_swap_b32_e32 v181, v182
	v_cvt_pk_bf16_f32 v184, v127, v129
	v_cvt_pk_bf16_f32 v185, v125, v128
	v_cvt_pk_bf16_f32 v186, v123, v126
	v_cvt_pk_bf16_f32 v187, v122, v124
	v_cvt_pk_bf16_f32 v212, v119, v121
	v_cvt_pk_bf16_f32 v213, v117, v120
	v_cvt_pk_bf16_f32 v214, v115, v118
	v_cvt_pk_bf16_f32 v215, v114, v116
	v_cvt_pk_bf16_f32 v216, v189, v190
	v_cvt_pk_bf16_f32 v217, v191, v192
	v_cvt_pk_bf16_f32 v218, v193, v194
	v_cvt_pk_bf16_f32 v219, v183, v195
	v_cvt_pk_bf16_f32 v220, v200, v201
	v_cvt_pk_bf16_f32 v221, v202, v188
	v_cvt_pk_bf16_f32 v222, v203, v204
	v_cvt_pk_bf16_f32 v223, v205, v179
	s_nop 0
	v_permlane32_swap_b32_e32 v184, v186
	v_permlane32_swap_b32_e32 v185, v187
	v_permlane32_swap_b32_e32 v212, v214
	v_permlane32_swap_b32_e32 v213, v215
	v_permlane32_swap_b32_e32 v216, v218
	v_permlane32_swap_b32_e32 v217, v219
	v_permlane32_swap_b32_e32 v220, v222
	v_permlane32_swap_b32_e32 v221, v223
	v_add_u32_e32 v118, 0x20000, v176
	v_add_u32_e32 v122, 0x30000, v176
	global_load_dwordx4 v[114:117], v118, s[58:59]
	s_nop 0
	global_load_dwordx4 v[118:121], v118, s[28:29]
	s_nop 0
	global_load_dwordx4 v[126:129], v122, s[58:59]
	s_nop 0
	global_load_dwordx4 v[122:125], v122, s[28:29]
	ds_read_b64_tr_b16 v[224:225], v159 offset:0
	ds_read_b64_tr_b16 v[226:227], v159 offset:0x800
	ds_read_b64_tr_b16 v[228:229], v159 offset:0x1000
	ds_read_b64_tr_b16 v[230:231], v159 offset:0x1800
	ds_read_b64_tr_b16 v[232:233], v159 offset:0x2000
	ds_read_b64_tr_b16 v[234:235], v159 offset:0x2800
	ds_read_b64_tr_b16 v[236:237], v159 offset:0x3000
	ds_read_b64_tr_b16 v[238:239], v159 offset:0x3800
	s_waitcnt lgkmcnt(0)
	s_nop 0
	v_mfma_f32_32x32x16_bf16 v[48:63], v[184:187], v[224:227], v[48:63]
	ds_read_b64_tr_b16 v[224:225], v159 offset:0x200
	ds_read_b64_tr_b16 v[226:227], v159 offset:0xa00
	v_max_f32_e32 v255, v81, v81
	v_max_f32_e32 v210, v80, v80
	v_max_f32_e32 v255, v210, v255
	v_max3_f32 v255, v255, v82, v83
	v_max3_f32 v255, v255, v84, v85
	v_mfma_f32_32x32x16_bf16 v[48:63], v[212:215], v[228:231], v[48:63]
	ds_read_b64_tr_b16 v[228:229], v159 offset:0x1200
	ds_read_b64_tr_b16 v[230:231], v159 offset:0x1a00
	v_max3_f32 v255, v255, v86, v87
	v_max3_f32 v255, v255, v88, v89
	v_max3_f32 v255, v255, v90, v91
	v_max3_f32 v255, v255, v92, v93
	v_max3_f32 v255, v255, v94, v95
	v_mfma_f32_32x32x16_bf16 v[48:63], v[216:219], v[232:235], v[48:63]
	ds_read_b64_tr_b16 v[232:233], v159 offset:0x2200
	ds_read_b64_tr_b16 v[234:235], v159 offset:0x2a00
	v_max3_f32 v255, v255, v64, v65
	v_max3_f32 v255, v255, v66, v67
	v_max3_f32 v255, v255, v68, v69
	v_max3_f32 v255, v255, v70, v71
	v_max3_f32 v255, v255, v72, v73
	v_mfma_f32_32x32x16_bf16 v[48:63], v[220:223], v[236:239], v[48:63]
	ds_read_b64_tr_b16 v[236:237], v159 offset:0x3200
	ds_read_b64_tr_b16 v[238:239], v159 offset:0x3a00
	v_max3_f32 v255, v255, v74, v75
	v_max3_f32 v255, v255, v76, v77
	v_max3_f32 v255, v255, v78, v79
	v_mov_b32_e32 v210, v255
	s_nop 1
	v_permlane32_swap_b32_e32 v255, v210
	s_waitcnt lgkmcnt(0)
; #define SWRITE(b, i) do { *(bf16x8*)(V_lds + (b) * SHM_V + vst0) = sr_[i].vs0;          \
;     *(bf16x8*)(V_lds + (b) * SHM_V + vst1) = sr_[i].vs1; int kc = sc * 2;               \
;     *(bf16x8*)(K_lds + (b) * SHM_K + KSWZ(sr, kc)) = sr_[i].ks0;                       \
;     *(bf16x8*)(K_lds + (b) * SHM_K + KSWZ(32 + sr, kc)) = sr_[i].ks1; } while (0)
; #define SWAIT() asm volatile("s_waitcnt vmcnt(0)" ::: "memory")
; #define RESC(a) do { if (__any((a) < 1.f)) { if (hi == 0) al_l[r32] = (a); asm volatile("s_waitcnt lgkmcnt(0)" ::: "memory"); \
;     _Pragma("unroll") for (int d = 0; d < 4; ++d) _Pragma("unroll") for (int r = 0; r < 16; ++r) o[d][r] *= al_l[crow(r, hi)]; } } while (0)
; __device__ __forceinline__ void partialSM(f32x16& p0, f32x16& p1, float& m_reg, float& mn, float& alpha) {
;     constexpr float C = SCALE * 1.4426950408889634f;
;     float pmax = p0[0];
; #pragma unroll
;     for (int r = 1; r < 16; ++r) pmax = fmaxf(pmax, p0[r]);
; #pragma unroll
;     for (int r = 0; r < 16; ++r) pmax = fmaxf(pmax, p1[r]);
;     { auto rr = __builtin_amdgcn_permlane32_swap(__float_as_uint(pmax), __float_as_uint(pmax), false, false);
;       pmax = fmaxf(__uint_as_float(rr[0]), __uint_as_float(rr[1])); }
;     if (__builtin_expect(__all(pmax - m_reg <= THR / SCALE), 1)) { mn = m_reg; alpha = 1.f; }
;     else { mn = fmaxf(m_reg, pmax); alpha = __builtin_amdgcn_exp2f((m_reg - mn) * C); m_reg = mn; }
;     const float mnC = -mn * C;
; #pragma unroll
;     for (int r = 0; r < 16; ++r) p0[r] = fmaf(p0[r], C, mnC);
; #pragma unroll
;     for (int r = 0; r < 16; ++r) p1[r] = fmaf(p1[r], C, mnC);
; #pragma unroll
;     for (int r = 0; r < 16; ++r) p0[r] = __builtin_amdgcn_exp2f(p0[r]);
; }
; __device__ __forceinline__ void attn_unit(const bf16_t* Qb, const bf16_t* Kh, const bf16_t* Vh, bf16_t* Ob, float* scr, int seq, float lam, float onemli, const float* subg, char* lds) {
;     ...
;             pv_d0(o, vb0 + (int)SHM_V, pa0, pa1, pa2, pa3); partialSM(pA0, pA1, m_reg, mnA, alA);
;             __syncthreads(); SWAIT(); SWRITE(1, SO);
;             RESC(alA); __syncthreads();
	v_mfma_f32_32x32x16_bf16 v[32:47], v[184:187], v[224:227], v[32:47]
	ds_read_b64_tr_b16 v[224:225], v159 offset:0x400
	ds_read_b64_tr_b16 v[226:227], v159 offset:0xc00
	v_max_f32_e32 v210, v210, v210
	v_max_f32_e32 v255, v255, v255
	v_max_f32_e32 v255, v255, v210
	v_sub_f32_e32 v210, v255, v175
	v_cmp_ge_f32_e32 vcc, s65, v210
	v_mfma_f32_32x32x16_bf16 v[32:47], v[212:215], v[228:231], v[32:47]
	ds_read_b64_tr_b16 v[228:229], v159 offset:0x1400
	ds_read_b64_tr_b16 v[230:231], v159 offset:0x1c00
	v_max_f32_e32 v210, v175, v175
	v_max_f32_e32 v210, v210, v255
	v_sub_f32_e32 v255, v175, v210
	v_mul_f32_e32 v255, 0x3e38aa3b, v255
	v_exp_f32_e32 v255, v255
	v_mfma_f32_32x32x16_bf16 v[32:47], v[216:219], v[232:235], v[32:47]
	ds_read_b64_tr_b16 v[232:233], v159 offset:0x2400
	ds_read_b64_tr_b16 v[234:235], v159 offset:0x2c00
	s_cmp_eq_u64 vcc, exec
	s_cselect_b64 s[8:9], -1, 0
	v_cndmask_b32_e64 v255, v255, 1.0, s[8:9]
	v_cndmask_b32_e64 v175, v210, v175, s[8:9]
	v_mul_f32_e32 v210, 0xbe38aa3b, v175
	v_mfma_f32_32x32x16_bf16 v[32:47], v[220:223], v[236:239], v[32:47]
	ds_read_b64_tr_b16 v[236:237], v159 offset:0x3400
	ds_read_b64_tr_b16 v[238:239], v159 offset:0x3c00
	v_pk_fma_f32 v[80:81], v[80:81], s[72:73], v[210:211] op_sel_hi:[1,0,0]
	v_pk_fma_f32 v[82:83], v[82:83], s[72:73], v[210:211] op_sel_hi:[1,0,0]
	v_pk_fma_f32 v[84:85], v[84:85], s[72:73], v[210:211] op_sel_hi:[1,0,0]
	v_pk_fma_f32 v[86:87], v[86:87], s[72:73], v[210:211] op_sel_hi:[1,0,0]
	v_pk_fma_f32 v[88:89], v[88:89], s[72:73], v[210:211] op_sel_hi:[1,0,0]
	s_waitcnt lgkmcnt(0)
	v_mfma_f32_32x32x16_bf16 v[16:31], v[184:187], v[224:227], v[16:31]
	ds_read_b64_tr_b16 v[224:225], v159 offset:0x600
	ds_read_b64_tr_b16 v[226:227], v159 offset:0xe00
	v_pk_fma_f32 v[90:91], v[90:91], s[72:73], v[210:211] op_sel_hi:[1,0,0]
	v_pk_fma_f32 v[92:93], v[92:93], s[72:73], v[210:211] op_sel_hi:[1,0,0]
	v_pk_fma_f32 v[94:95], v[94:95], s[72:73], v[210:211] op_sel_hi:[1,0,0]
	v_exp_f32_e32 v240, v80
	v_mfma_f32_32x32x16_bf16 v[16:31], v[212:215], v[228:231], v[16:31]
	ds_read_b64_tr_b16 v[228:229], v159 offset:0x1600
	ds_read_b64_tr_b16 v[230:231], v159 offset:0x1e00
	v_exp_f32_e32 v241, v81
	v_exp_f32_e32 v242, v82
	v_exp_f32_e32 v243, v83
	v_mfma_f32_32x32x16_bf16 v[16:31], v[216:219], v[232:235], v[16:31]
	ds_read_b64_tr_b16 v[232:233], v159 offset:0x2600
	ds_read_b64_tr_b16 v[234:235], v159 offset:0x2e00
	v_exp_f32_e32 v244, v84
	v_exp_f32_e32 v245, v85
	v_exp_f32_e32 v246, v86
	v_mfma_f32_32x32x16_bf16 v[16:31], v[220:223], v[236:239], v[16:31]
	ds_read_b64_tr_b16 v[236:237], v159 offset:0x3600
	ds_read_b64_tr_b16 v[238:239], v159 offset:0x3e00
	v_exp_f32_e32 v247, v87
	v_exp_f32_e32 v248, v88
	v_exp_f32_e32 v249, v89
	s_waitcnt lgkmcnt(0)
	v_mfma_f32_32x32x16_bf16 v[0:15], v[184:187], v[224:227], v[0:15]
	s_barrier
	s_waitcnt vmcnt(0)
	s_waitcnt vmcnt(3)
	ds_write_b128 v163, v[114:117] offset:16384
	s_waitcnt vmcnt(1)
	ds_write_b128 v164, v[126:129] offset:16384
	ds_write_b128 v161, v[118:121] offset:49152
	s_waitcnt vmcnt(0)
	ds_write_b128 v162, v[122:125] offset:49152
	v_exp_f32_e32 v250, v90
	v_exp_f32_e32 v251, v91
	v_exp_f32_e32 v206, v92
	v_mfma_f32_32x32x16_bf16 v[0:15], v[212:215], v[228:231], v[0:15]
	v_exp_f32_e32 v207, v93
	v_exp_f32_e32 v208, v94
	v_exp_f32_e32 v209, v95
	v_mfma_f32_32x32x16_bf16 v[0:15], v[216:219], v[232:235], v[0:15]
	v_mfma_f32_32x32x16_bf16 v[0:15], v[220:223], v[236:239], v[0:15]
	v_mov_b32_e32 v179, v255
	v_cmp_gt_f32_e32 vcc, 1.0, v179
	s_cbranch_vccz .LBB0_270
	s_and_saveexec_b64 s[2:3], s[6:7]
	ds_write_b32 v157, v179 offset:128
	s_or_b64 exec, exec, s[2:3]
	s_waitcnt lgkmcnt(0)
	ds_read_b128 v[114:117], v158 offset:224
	ds_read_b128 v[118:121], v158 offset:192
	ds_read_b128 v[122:125], v158 offset:160
	ds_read_b128 v[126:129], v158 offset:128
	s_waitcnt lgkmcnt(3)
	v_pk_mul_f32 v[62:63], v[62:63], v[116:117]
	s_waitcnt lgkmcnt(2)
	v_pk_mul_f32 v[58:59], v[58:59], v[120:121]
	s_waitcnt lgkmcnt(1)
	v_pk_mul_f32 v[54:55], v[54:55], v[124:125]
	s_waitcnt lgkmcnt(0)
	v_pk_mul_f32 v[50:51], v[50:51], v[128:129]
	v_pk_mul_f32 v[60:61], v[60:61], v[114:115]
	v_pk_mul_f32 v[56:57], v[56:57], v[118:119]
	v_pk_mul_f32 v[52:53], v[52:53], v[122:123]
	v_pk_mul_f32 v[48:49], v[48:49], v[126:127]
	v_pk_mul_f32 v[46:47], v[46:47], v[116:117]
	v_pk_mul_f32 v[42:43], v[42:43], v[120:121]
	v_pk_mul_f32 v[38:39], v[38:39], v[124:125]
	v_pk_mul_f32 v[34:35], v[34:35], v[128:129]
	v_pk_mul_f32 v[44:45], v[44:45], v[114:115]
	v_pk_mul_f32 v[40:41], v[40:41], v[118:119]
	v_pk_mul_f32 v[36:37], v[36:37], v[122:123]
	v_pk_mul_f32 v[32:33], v[32:33], v[126:127]
	v_pk_mul_f32 v[30:31], v[30:31], v[116:117]
	v_pk_mul_f32 v[26:27], v[26:27], v[120:121]
	v_pk_mul_f32 v[22:23], v[22:23], v[124:125]
	v_pk_mul_f32 v[18:19], v[18:19], v[128:129]
	v_pk_mul_f32 v[28:29], v[28:29], v[114:115]
	v_pk_mul_f32 v[24:25], v[24:25], v[118:119]
	v_pk_mul_f32 v[20:21], v[20:21], v[122:123]
	v_pk_mul_f32 v[16:17], v[16:17], v[126:127]
	v_pk_mul_f32 v[14:15], v[14:15], v[116:117]
	v_pk_mul_f32 v[10:11], v[10:11], v[120:121]
	v_pk_mul_f32 v[6:7], v[6:7], v[124:125]
	v_pk_mul_f32 v[2:3], v[2:3], v[128:129]
	v_pk_mul_f32 v[12:13], v[12:13], v[114:115]
	v_pk_mul_f32 v[8:9], v[8:9], v[118:119]
	v_pk_mul_f32 v[4:5], v[4:5], v[122:123]
	v_pk_mul_f32 v[0:1], v[0:1], v[126:127]

; __device__ __forceinline__ void partialSM(f32x16& p0, f32x16& p1, float& m_reg, float& mn, float& alpha) {
;     constexpr float C = SCALE * 1.4426950408889634f;
;     float pmax = p0[0];
; #pragma unroll
;     for (int r = 1; r < 16; ++r) pmax = fmaxf(pmax, p0[r]);
; #pragma unroll
;     for (int r = 0; r < 16; ++r) pmax = fmaxf(pmax, p1[r]);
;     { auto rr = __builtin_amdgcn_permlane32_swap(__float_as_uint(pmax), __float_as_uint(pmax), false, false);
;       pmax = fmaxf(__uint_as_float(rr[0]), __uint_as_float(rr[1])); }
; __device__ __forceinline__ void finishSM(f32x16& p0, f32x16& p1, float alpha, float& l_reg, bf16x8& pa0, bf16x8& pa1, bf16x8& pa2, bf16x8& pa3) {
; #pragma unroll
;     for (int r = 0; r < 16; ++r) p1[r] = __builtin_amdgcn_exp2f(p1[r]);
;     float ps = 0;
; #pragma unroll
;     for (int r = 0; r < 16; ++r) ps += p0[r];
; #pragma unroll
;     for (int r = 0; r < 16; ++r) ps += p1[r];
;     { auto rr = __builtin_amdgcn_permlane32_swap(__float_as_uint(ps), __float_as_uint(ps), false, false);
;       ps = __uint_as_float(rr[0]) + __uint_as_float(rr[1]); }
;     l_reg = l_reg * alpha + ps;
;     ...
;     PK4(p0, 0, pa0); PK4(p0, 8, pa1); PK4(p1, 0, pa2); PK4(p1, 8, pa3);
;     ...
; }
; __device__ __forceinline__ void qkt(f32x16& p0, f32x16& p1, const char* Ks, const bf16x8* qr, int r32, int hi, int comp) {
;     p0 = f32x16{}; p1 = f32x16{};
; #pragma unroll
;     for (int d0 = 0; d0 < 4; ++d0) { const int cb = (comp * 64 + d0 * 16 + hi * 8) * 2;
;         const bf16x8 b0 = *reinterpret_cast<const bf16x8*>(Ks + KSWZ(r32, cb));
;         const bf16x8 b1 = *reinterpret_cast<const bf16x8*>(Ks + KSWZ(32 + r32, cb));
;         p0 = __builtin_amdgcn_mfma_f32_32x32x16_bf16(b0, qr[d0], p0, 0, 0, 0);
;         p1 = __builtin_amdgcn_mfma_f32_32x32x16_bf16(b1, qr[d0], p1, 0, 0, 0); }
; }
; __device__ __forceinline__ int v_st(int k, int c) { const int kk = (k & ~0xC) | ((k & 4) << 1) | ((k & 8) >> 1); return ((kk >> 3) * 4 + (c >> 5)) * 512 + ((kk & 7) * 32 + (c & 31)) * 2; }
; __device__ __forceinline__ int v_rd_base(int lane) { return ((lane & 3) << 3) | (((lane >> 2) & 3) << 6) | (((lane >> 4) & 1) << 5) | (((lane >> 5) & 1) << 8); }
; template <int OFF> __device__ __forceinline__ s16x4 tr_read(int vb) {
;     s16x4 r; asm volatile("ds_read_b64_tr_b16 %0, %1 offset:%2" : "=&v"(r) : "v"(vb), "i"(OFF) : "memory"); return r;
; }
.LBB0_280:
	ds_read_b128 v[64:67], v140 offset:49152
	ds_read_b128 v[68:71], v140 offset:57344
	v_add_f32_e32 v135, 0, v240
	v_add_f32_e32 v135, v241, v135
	v_add_f32_e32 v135, v242, v135
	s_waitcnt lgkmcnt(1)
	v_mfma_f32_32x32x16_bf16 v[80:95], v[64:67], v[110:113], 0
	v_add_f32_e32 v135, v243, v135
	v_add_f32_e32 v135, v244, v135
	ds_read_b128 v[136:139], v143 offset:49152
	ds_read_b128 v[178:181], v143 offset:57344
	v_add_f32_e32 v135, v245, v135
	v_add_f32_e32 v135, v246, v135
	v_add_f32_e32 v135, v247, v135
	v_add_f32_e32 v135, v248, v135
	s_waitcnt lgkmcnt(2)
	v_mfma_f32_32x32x16_bf16 v[64:79], v[68:71], v[110:113], 0
	v_add_f32_e32 v135, v249, v135
	v_add_f32_e32 v135, v250, v135
	v_add_f32_e32 v135, v251, v135
	v_exp_f32_e32 v128, v128
	v_add_f32_e32 v135, v206, v135
	v_exp_f32_e32 v129, v129
	v_add_f32_e32 v135, v207, v135
	s_waitcnt lgkmcnt(1)
	v_mfma_f32_32x32x16_bf16 v[80:95], v[136:139], v[106:109], v[80:95]
	v_exp_f32_e32 v126, v126
	v_add_f32_e32 v135, v208, v135
	v_exp_f32_e32 v127, v127
	v_add_f32_e32 v135, v209, v135
	v_exp_f32_e32 v122, v122
	v_add_f32_e32 v135, v128, v135
	v_exp_f32_e32 v123, v123
	s_waitcnt lgkmcnt(0)
	v_mfma_f32_32x32x16_bf16 v[64:79], v[178:181], v[106:109], v[64:79]
	ds_read_b128 v[136:139], v142 offset:49152
	ds_read_b128 v[178:181], v142 offset:57344
	v_add_f32_e32 v135, v129, v135
	v_exp_f32_e32 v118, v118
	v_add_f32_e32 v135, v126, v135
	v_exp_f32_e32 v119, v119
	v_add_f32_e32 v135, v127, v135
	v_exp_f32_e32 v116, v116
	s_waitcnt lgkmcnt(1)
	v_mfma_f32_32x32x16_bf16 v[80:95], v[136:139], v[102:105], v[80:95]
	v_add_f32_e32 v135, v122, v135
	v_exp_f32_e32 v117, v117
	v_add_f32_e32 v135, v123, v135
	v_exp_f32_e32 v124, v124
	v_add_f32_e32 v135, v118, v135
	v_exp_f32_e32 v125, v125
	v_add_f32_e32 v135, v119, v135
	s_waitcnt lgkmcnt(0)
	v_mfma_f32_32x32x16_bf16 v[64:79], v[178:181], v[102:105], v[64:79]
	ds_read_b128 v[136:139], v141 offset:49152
	ds_read_b128 v[178:181], v141 offset:57344
	v_exp_f32_e32 v120, v120
	v_add_f32_e32 v135, v116, v135
	v_exp_f32_e32 v121, v121
	v_add_f32_e32 v135, v117, v135
	v_exp_f32_e32 v114, v114
	v_add_f32_e32 v135, v124, v135
	s_waitcnt lgkmcnt(1)
	v_mfma_f32_32x32x16_bf16 v[80:95], v[136:139], v[98:101], v[80:95]
	v_exp_f32_e32 v115, v115
	v_add_f32_e32 v135, v125, v135
	v_add_f32_e32 v135, v120, v135
	v_add_f32_e32 v135, v121, v135
	v_add_f32_e32 v135, v114, v135
	v_add_f32_e32 v135, v115, v135
	v_mov_b32_e32 v136, v135
	s_waitcnt lgkmcnt(0)
	v_mfma_f32_32x32x16_bf16 v[64:79], v[178:181], v[98:101], v[64:79]
	v_permlane32_swap_b32_e32 v135, v136
	v_cvt_pk_bf16_f32 v178, v240, v241
	v_cvt_pk_bf16_f32 v179, v242, v243
	v_cvt_pk_bf16_f32 v180, v244, v245
	v_cvt_pk_bf16_f32 v181, v246, v247
	v_cvt_pk_bf16_f32 v144, v248, v249
	v_cvt_pk_bf16_f32 v145, v250, v251
	v_cvt_pk_bf16_f32 v146, v206, v207
	v_cvt_pk_bf16_f32 v147, v208, v209
	v_cvt_pk_bf16_f32 v166, v128, v129
	v_cvt_pk_bf16_f32 v167, v126, v127
	v_cvt_pk_bf16_f32 v168, v122, v123
	v_cvt_pk_bf16_f32 v169, v118, v119
	v_cvt_pk_bf16_f32 v170, v116, v117
	v_cvt_pk_bf16_f32 v171, v124, v125
	v_cvt_pk_bf16_f32 v172, v120, v121
	v_cvt_pk_bf16_f32 v173, v114, v115
	s_nop 0
	v_permlane32_swap_b32_e32 v178, v180
	v_permlane32_swap_b32_e32 v179, v181
	v_permlane32_swap_b32_e32 v144, v146
	v_permlane32_swap_b32_e32 v145, v147
	v_permlane32_swap_b32_e32 v166, v168
	v_permlane32_swap_b32_e32 v167, v169
	v_permlane32_swap_b32_e32 v170, v172
	v_permlane32_swap_b32_e32 v171, v173
	v_add_u32_e32 v122, 0x10000, v96
	global_load_dwordx4 v[240:243], v96, s[58:59]
	global_load_dwordx4 v[244:247], v96, s[28:29]
	global_load_dwordx4 v[206:209], v122, s[58:59]
	s_nop 0
	global_load_dwordx4 v[248:251], v122, s[28:29]
	ds_read_b64_tr_b16 v[174:175], v160 offset:0
	ds_read_b64_tr_b16 v[176:177], v160 offset:0x800
	ds_read_b64_tr_b16 v[182:183], v160 offset:0x1000
	ds_read_b64_tr_b16 v[184:185], v160 offset:0x1800
	ds_read_b64_tr_b16 v[186:187], v160 offset:0x2000
	ds_read_b64_tr_b16 v[188:189], v160 offset:0x2800
	ds_read_b64_tr_b16 v[212:213], v160 offset:0x3000
	ds_read_b64_tr_b16 v[214:215], v160 offset:0x3800
	s_waitcnt lgkmcnt(0)
	s_nop 0
	v_mfma_f32_32x32x16_bf16 v[48:63], v[178:181], v[174:177], v[48:63]
	ds_read_b64_tr_b16 v[174:175], v160 offset:0x200
	ds_read_b64_tr_b16 v[176:177], v160 offset:0xa00
	v_max_f32_e32 v137, v81, v81
	v_max_f32_e32 v138, v80, v80
	v_max_f32_e32 v137, v138, v137
	v_max3_f32 v137, v137, v82, v83
	v_max3_f32 v137, v137, v84, v85
	v_mfma_f32_32x32x16_bf16 v[48:63], v[144:147], v[182:185], v[48:63]
	ds_read_b64_tr_b16 v[182:183], v160 offset:0x1200
	ds_read_b64_tr_b16 v[184:185], v160 offset:0x1a00
	v_max3_f32 v137, v137, v86, v87
	v_max3_f32 v137, v137, v88, v89
	v_max3_f32 v137, v137, v90, v91
	v_max3_f32 v137, v137, v92, v93
	v_max3_f32 v137, v137, v94, v95
	v_mfma_f32_32x32x16_bf16 v[48:63], v[166:169], v[186:189], v[48:63]
	ds_read_b64_tr_b16 v[186:187], v160 offset:0x2200
	ds_read_b64_tr_b16 v[188:189], v160 offset:0x2a00
	v_max3_f32 v137, v137, v64, v65
	v_max3_f32 v137, v137, v66, v67
	v_max3_f32 v137, v137, v68, v69
	v_max3_f32 v137, v137, v70, v71
	v_max3_f32 v137, v137, v72, v73
	v_mfma_f32_32x32x16_bf16 v[48:63], v[170:173], v[212:215], v[48:63]
	ds_read_b64_tr_b16 v[212:213], v160 offset:0x3200
	ds_read_b64_tr_b16 v[214:215], v160 offset:0x3a00
	v_max3_f32 v137, v137, v74, v75
	v_max3_f32 v137, v137, v76, v77
	v_max3_f32 v137, v137, v78, v79
	v_mov_b32_e32 v138, v137
	s_nop 1
	v_permlane32_swap_b32_e32 v137, v138
	s_waitcnt lgkmcnt(0)
; #define SBAR() __builtin_amdgcn_sched_barrier(0)
; #define SWRITE(b, i) do { *(bf16x8*)(V_lds + (b) * SHM_V + vst0) = sr_[i].vs0;          \
;     *(bf16x8*)(V_lds + (b) * SHM_V + vst1) = sr_[i].vs1; int kc = sc * 2;               \
;     *(bf16x8*)(K_lds + (b) * SHM_K + KSWZ(sr, kc)) = sr_[i].ks0;                       \
;     *(bf16x8*)(K_lds + (b) * SHM_K + KSWZ(32 + sr, kc)) = sr_[i].ks1; } while (0)
; #define SWAIT() asm volatile("s_waitcnt vmcnt(0)" ::: "memory")
; #define RESC(a) do { if (__any((a) < 1.f)) { if (hi == 0) al_l[r32] = (a); asm volatile("s_waitcnt lgkmcnt(0)" ::: "memory"); \
;     _Pragma("unroll") for (int d = 0; d < 4; ++d) _Pragma("unroll") for (int r = 0; r < 16; ++r) o[d][r] *= al_l[crow(r, hi)]; } } while (0)
; __device__ __forceinline__ void partialSM(f32x16& p0, f32x16& p1, float& m_reg, float& mn, float& alpha) {
;     ...
;     if (__builtin_expect(__all(pmax - m_reg <= THR / SCALE), 1)) { mn = m_reg; alpha = 1.f; }
;     else { mn = fmaxf(m_reg, pmax); alpha = __builtin_amdgcn_exp2f((m_reg - mn) * C); m_reg = mn; }
;     const float mnC = -mn * C;
; #pragma unroll
;     for (int r = 0; r < 16; ++r) p0[r] = fmaf(p0[r], C, mnC);
; #pragma unroll
;     for (int r = 0; r < 16; ++r) p1[r] = fmaf(p1[r], C, mnC);
; #pragma unroll
;     for (int r = 0; r < 16; ++r) p0[r] = __builtin_amdgcn_exp2f(p0[r]);
; __device__ __forceinline__ void attn_unit(const bf16_t* Qb, const bf16_t* Kh, const bf16_t* Vh, bf16_t* Ob, float* scr, int seq, float lam, float onemli, const float* subg, char* lds) {
;     ...
;         f32x16 pA0, pA1, pB0, pB1; float mnA, mnB, alA, alB; bf16x8 pa0, pa1, pa2, pa3;
;         constexpr int SE = 0, SO = 0;
;         __syncthreads();
;         SLOAD(SE, 0); asm volatile("s_waitcnt vmcnt(0)" ::: "memory"); SWRITE(0, SE); __syncthreads();
;         qkt(pA0, pA1, K_lds, qr, r32, hi, comp); partialSM(pA0, pA1, m_reg, mnA, alA);
;         SLOAD(SO, KVBLK);
;         SWAIT(); SWRITE(1, SO); __syncthreads();
;         for (int j = 1; j + 1 < NT; j += 2) {
;             SBAR(); qkt(pB0, pB1, K_lds + SHM_K, qr, r32, hi, comp);
;             finishSM(pA0, pA1, alA, l_reg, pa0, pa1, pa2, pa3); SBAR();
;             SLOAD(SO, (j + 1) * KVBLK); SBAR();
;             pv_d0(o, vb0, pa0, pa1, pa2, pa3); partialSM(pB0, pB1, m_reg, mnB, alB);
;             __syncthreads(); SWAIT(); SWRITE(0, SE);
;             RESC(alB); __syncthreads();
	v_mfma_f32_32x32x16_bf16 v[32:47], v[178:181], v[174:177], v[32:47]
	ds_read_b64_tr_b16 v[174:175], v160 offset:0x400
	ds_read_b64_tr_b16 v[176:177], v160 offset:0xc00
	v_max_f32_e32 v138, v138, v138
	v_max_f32_e32 v137, v137, v137
	v_max_f32_e32 v137, v137, v138
	v_sub_f32_e32 v138, v137, v134
	v_cmp_ge_f32_e32 vcc, s65, v138
	v_mfma_f32_32x32x16_bf16 v[32:47], v[144:147], v[182:185], v[32:47]
	ds_read_b64_tr_b16 v[182:183], v160 offset:0x1400
	ds_read_b64_tr_b16 v[184:185], v160 offset:0x1c00
	v_max_f32_e32 v138, v134, v134
	v_max_f32_e32 v137, v138, v137
	v_sub_f32_e32 v138, v134, v137
	v_mul_f32_e32 v138, 0x3e38aa3b, v138
	v_exp_f32_e32 v138, v138
	v_mfma_f32_32x32x16_bf16 v[32:47], v[166:169], v[186:189], v[32:47]
	ds_read_b64_tr_b16 v[186:187], v160 offset:0x2400
	ds_read_b64_tr_b16 v[188:189], v160 offset:0x2c00
	s_cmp_eq_u64 vcc, exec
	s_cselect_b64 s[8:9], -1, 0
	v_cndmask_b32_e64 v138, v138, 1.0, s[8:9]
	v_cndmask_b32_e64 v134, v137, v134, s[8:9]
	v_mul_f32_e32 v137, 0xbe38aa3b, v134
	v_mfma_f32_32x32x16_bf16 v[32:47], v[170:173], v[212:215], v[32:47]
	ds_read_b64_tr_b16 v[212:213], v160 offset:0x3400
	ds_read_b64_tr_b16 v[214:215], v160 offset:0x3c00
	v_pk_fma_f32 v[80:81], v[80:81], s[72:73], v[136:137] op_sel:[0,0,1] op_sel_hi:[1,0,1]
	v_pk_fma_f32 v[82:83], v[82:83], s[72:73], v[136:137] op_sel:[0,0,1] op_sel_hi:[1,0,1]
	v_pk_fma_f32 v[84:85], v[84:85], s[72:73], v[136:137] op_sel:[0,0,1] op_sel_hi:[1,0,1]
	v_pk_fma_f32 v[86:87], v[86:87], s[72:73], v[136:137] op_sel:[0,0,1] op_sel_hi:[1,0,1]
	v_pk_fma_f32 v[88:89], v[88:89], s[72:73], v[136:137] op_sel:[0,0,1] op_sel_hi:[1,0,1]
	s_waitcnt lgkmcnt(0)
	v_mfma_f32_32x32x16_bf16 v[16:31], v[178:181], v[174:177], v[16:31]
	ds_read_b64_tr_b16 v[174:175], v160 offset:0x600
	ds_read_b64_tr_b16 v[176:177], v160 offset:0xe00
	v_pk_fma_f32 v[90:91], v[90:91], s[72:73], v[136:137] op_sel:[0,0,1] op_sel_hi:[1,0,1]
	v_pk_fma_f32 v[92:93], v[92:93], s[72:73], v[136:137] op_sel:[0,0,1] op_sel_hi:[1,0,1]
	v_pk_fma_f32 v[94:95], v[94:95], s[72:73], v[136:137] op_sel:[0,0,1] op_sel_hi:[1,0,1]
	v_exp_f32_e32 v127, v80
	v_mfma_f32_32x32x16_bf16 v[16:31], v[144:147], v[182:185], v[16:31]
	ds_read_b64_tr_b16 v[182:183], v160 offset:0x1600
	ds_read_b64_tr_b16 v[184:185], v160 offset:0x1e00
	v_exp_f32_e32 v129, v81
	v_exp_f32_e32 v125, v82
	v_exp_f32_e32 v128, v83
	v_mfma_f32_32x32x16_bf16 v[16:31], v[166:169], v[186:189], v[16:31]
	ds_read_b64_tr_b16 v[186:187], v160 offset:0x2600
	ds_read_b64_tr_b16 v[188:189], v160 offset:0x2e00
	v_exp_f32_e32 v123, v84
	v_exp_f32_e32 v126, v85
	v_exp_f32_e32 v122, v86
	v_mfma_f32_32x32x16_bf16 v[16:31], v[170:173], v[212:215], v[16:31]
	ds_read_b64_tr_b16 v[212:213], v160 offset:0x3600
	ds_read_b64_tr_b16 v[214:215], v160 offset:0x3e00
	v_exp_f32_e32 v124, v87
	v_exp_f32_e32 v119, v88
	v_exp_f32_e32 v121, v89
	s_waitcnt lgkmcnt(0)
	v_mfma_f32_32x32x16_bf16 v[0:15], v[178:181], v[174:177], v[0:15]
	s_barrier
	s_waitcnt vmcnt(0)
	s_waitcnt vmcnt(3)
	ds_write_b128 v163, v[240:243]
	s_waitcnt vmcnt(1)
	ds_write_b128 v164, v[206:209]
	ds_write_b128 v161, v[244:247] offset:32768
	s_waitcnt vmcnt(0)
	ds_write_b128 v162, v[248:251] offset:32768
	v_exp_f32_e32 v117, v90
	v_exp_f32_e32 v120, v91
	v_exp_f32_e32 v115, v92
	v_mfma_f32_32x32x16_bf16 v[0:15], v[144:147], v[182:185], v[0:15]
	v_exp_f32_e32 v118, v93
	v_exp_f32_e32 v114, v94
	v_exp_f32_e32 v116, v95
	v_mfma_f32_32x32x16_bf16 v[0:15], v[166:169], v[186:189], v[0:15]
	v_mfma_f32_32x32x16_bf16 v[0:15], v[170:173], v[212:215], v[0:15]
	v_cmp_gt_f32_e32 vcc, 1.0, v138
	s_cbranch_vccz .LBB0_284
	s_and_saveexec_b64 s[2:3], s[6:7]
	ds_write_b32 v157, v138 offset:128
	s_or_b64 exec, exec, s[2:3]
	s_waitcnt lgkmcnt(0)
	ds_read_b128 v[240:243], v158 offset:224
	ds_read_b128 v[244:247], v158 offset:192
	ds_read_b128 v[248:251], v158 offset:160
	ds_read_b128 v[206:209], v158 offset:128
	s_waitcnt lgkmcnt(3)
	v_pk_mul_f32 v[62:63], v[62:63], v[242:243]
	s_waitcnt lgkmcnt(2)
	v_pk_mul_f32 v[58:59], v[58:59], v[246:247]
	s_waitcnt lgkmcnt(1)
	v_pk_mul_f32 v[54:55], v[54:55], v[250:251]
	s_waitcnt lgkmcnt(0)
	v_pk_mul_f32 v[50:51], v[50:51], v[208:209]
	v_pk_mul_f32 v[60:61], v[60:61], v[240:241]
	v_pk_mul_f32 v[56:57], v[56:57], v[244:245]
	v_pk_mul_f32 v[52:53], v[52:53], v[248:249]
	v_pk_mul_f32 v[48:49], v[48:49], v[206:207]
	v_pk_mul_f32 v[46:47], v[46:47], v[242:243]
	v_pk_mul_f32 v[42:43], v[42:43], v[246:247]
	v_pk_mul_f32 v[38:39], v[38:39], v[250:251]
	v_pk_mul_f32 v[34:35], v[34:35], v[208:209]
	v_pk_mul_f32 v[44:45], v[44:45], v[240:241]
	v_pk_mul_f32 v[40:41], v[40:41], v[244:245]
	v_pk_mul_f32 v[36:37], v[36:37], v[248:249]
	v_pk_mul_f32 v[32:33], v[32:33], v[206:207]
	v_pk_mul_f32 v[30:31], v[30:31], v[242:243]
	v_pk_mul_f32 v[26:27], v[26:27], v[246:247]
	v_pk_mul_f32 v[22:23], v[22:23], v[250:251]
	v_pk_mul_f32 v[18:19], v[18:19], v[208:209]
	v_pk_mul_f32 v[28:29], v[28:29], v[240:241]
	v_pk_mul_f32 v[24:25], v[24:25], v[244:245]
	v_pk_mul_f32 v[20:21], v[20:21], v[248:249]
	v_pk_mul_f32 v[16:17], v[16:17], v[206:207]
	v_pk_mul_f32 v[14:15], v[14:15], v[242:243]
	v_pk_mul_f32 v[10:11], v[10:11], v[246:247]
	v_pk_mul_f32 v[6:7], v[6:7], v[250:251]
	v_pk_mul_f32 v[2:3], v[2:3], v[208:209]
	v_pk_mul_f32 v[12:13], v[12:13], v[240:241]
	v_pk_mul_f32 v[8:9], v[8:9], v[244:245]
	v_pk_mul_f32 v[4:5], v[4:5], v[248:249]
	v_pk_mul_f32 v[0:1], v[0:1], v[206:207]
; __device__ __forceinline__ void partialSM(f32x16& p0, f32x16& p1, float& m_reg, float& mn, float& alpha) {
;     constexpr float C = SCALE * 1.4426950408889634f;
;     float pmax = p0[0];
; #pragma unroll
;     for (int r = 1; r < 16; ++r) pmax = fmaxf(pmax, p0[r]);
; #pragma unroll
;     for (int r = 0; r < 16; ++r) pmax = fmaxf(pmax, p1[r]);
;     { auto rr = __builtin_amdgcn_permlane32_swap(__float_as_uint(pmax), __float_as_uint(pmax), false, false);
;       pmax = fmaxf(__uint_as_float(rr[0]), __uint_as_float(rr[1])); }
;     if (__builtin_expect(__all(pmax - m_reg <= THR / SCALE), 1)) { mn = m_reg; alpha = 1.f; }
;     else { mn = fmaxf(m_reg, pmax); alpha = __builtin_amdgcn_exp2f((m_reg - mn) * C); m_reg = mn; }
;     const float mnC = -mn * C;
; #pragma unroll
;     for (int r = 0; r < 16; ++r) p0[r] = fmaf(p0[r], C, mnC);
; #pragma unroll
;     for (int r = 0; r < 16; ++r) p1[r] = fmaf(p1[r], C, mnC);
; #pragma unroll
;     for (int r = 0; r < 16; ++r) p0[r] = __builtin_amdgcn_exp2f(p0[r]);
; }
; __device__ __forceinline__ void finishSM(f32x16& p0, f32x16& p1, float alpha, float& l_reg, bf16x8& pa0, bf16x8& pa1, bf16x8& pa2, bf16x8& pa3) {
; #pragma unroll
;     for (int r = 0; r < 16; ++r) p1[r] = __builtin_amdgcn_exp2f(p1[r]);
;     float ps = 0;
; #pragma unroll
;     for (int r = 0; r < 16; ++r) ps += p0[r];
; #pragma unroll
;     for (int r = 0; r < 16; ++r) ps += p1[r];
;     { auto rr = __builtin_amdgcn_permlane32_swap(__float_as_uint(ps), __float_as_uint(ps), false, false);
;       ps = __uint_as_float(rr[0]) + __uint_as_float(rr[1]); }
;     l_reg = l_reg * alpha + ps;
;     ...
;     PK4(p0, 0, pa0); PK4(p0, 8, pa1); PK4(p1, 0, pa2); PK4(p1, 8, pa3);
;     ...
; }
; __device__ __forceinline__ void qkt(f32x16& p0, f32x16& p1, const char* Ks, const bf16x8* qr, int r32, int hi, int comp) {
;     p0 = f32x16{}; p1 = f32x16{};
; #pragma unroll
;     for (int d0 = 0; d0 < 4; ++d0) { const int cb = (comp * 64 + d0 * 16 + hi * 8) * 2;
;         const bf16x8 b0 = *reinterpret_cast<const bf16x8*>(Ks + KSWZ(r32, cb));
;         const bf16x8 b1 = *reinterpret_cast<const bf16x8*>(Ks + KSWZ(32 + r32, cb));
;         p0 = __builtin_amdgcn_mfma_f32_32x32x16_bf16(b0, qr[d0], p0, 0, 0, 0);
;         p1 = __builtin_amdgcn_mfma_f32_32x32x16_bf16(b1, qr[d0], p1, 0, 0, 0); }
; }
.LBB0_284:
	v_fmamk_f32 v167, v64, 0x3e38aa3b, v137
	v_fmamk_f32 v168, v65, 0x3e38aa3b, v137
	v_fmamk_f32 v169, v66, 0x3e38aa3b, v137
	v_fmamk_f32 v170, v67, 0x3e38aa3b, v137
	v_fmamk_f32 v171, v68, 0x3e38aa3b, v137
	v_fmamk_f32 v144, v69, 0x3e38aa3b, v137
	v_fmamk_f32 v145, v70, 0x3e38aa3b, v137
	v_fmamk_f32 v146, v71, 0x3e38aa3b, v137
	v_fmamk_f32 v147, v72, 0x3e38aa3b, v137
	v_fmamk_f32 v148, v73, 0x3e38aa3b, v137
	v_fmamk_f32 v149, v74, 0x3e38aa3b, v137
	v_fmamk_f32 v166, v75, 0x3e38aa3b, v137
	v_fmamk_f32 v139, v76, 0x3e38aa3b, v137
	v_fmamk_f32 v172, v77, 0x3e38aa3b, v137
	v_fmamk_f32 v173, v78, 0x3e38aa3b, v137
	v_fmac_f32_e32 v137, 0x3e38aa3b, v79
	s_waitcnt lgkmcnt(0)
	s_barrier
	ds_read_b128 v[64:67], v140 offset:32768
	ds_read_b128 v[68:71], v140 offset:40960
	ds_read_b128 v[174:177], v143 offset:32768
	ds_read_b128 v[178:181], v143 offset:40960
	v_exp_f32_e32 v185, v139
	v_add_f32_e32 v139, 0, v127
	s_waitcnt lgkmcnt(3)
	v_mfma_f32_32x32x16_bf16 v[80:95], v[64:67], v[110:113], 0
	v_add_f32_e32 v139, v129, v139
	v_add_f32_e32 v139, v125, v139
	v_add_f32_e32 v139, v128, v139
	v_add_f32_e32 v139, v123, v139
	v_add_f32_e32 v139, v126, v139
	v_add_f32_e32 v139, v122, v139
	v_add_f32_e32 v139, v124, v139
	s_waitcnt lgkmcnt(2)
	v_mfma_f32_32x32x16_bf16 v[64:79], v[68:71], v[110:113], 0
	v_add_f32_e32 v139, v119, v139
	v_add_f32_e32 v139, v121, v139
	v_add_f32_e32 v139, v117, v139
	v_add_f32_e32 v139, v120, v139
	v_add_f32_e32 v139, v115, v139
	v_add_f32_e32 v139, v118, v139
	v_add_f32_e32 v139, v114, v139
	s_waitcnt lgkmcnt(1)
	v_mfma_f32_32x32x16_bf16 v[80:95], v[174:177], v[106:109], v[80:95]
	v_add_f32_e32 v139, v116, v139
	v_exp_f32_e32 v145, v145
	v_exp_f32_e32 v182, v148
	v_exp_f32_e32 v183, v149
	v_exp_f32_e32 v184, v166
	v_exp_f32_e32 v186, v172
	v_exp_f32_e32 v187, v173
	s_waitcnt lgkmcnt(0)
	v_mfma_f32_32x32x16_bf16 v[64:79], v[178:181], v[106:109], v[64:79]
	ds_read_b128 v[174:177], v142 offset:32768
	ds_read_b128 v[178:181], v142 offset:40960
	v_exp_f32_e32 v137, v137
	s_waitcnt lgkmcnt(1)
	v_mfma_f32_32x32x16_bf16 v[80:95], v[174:177], v[102:105], v[80:95]
	s_waitcnt lgkmcnt(0)
	v_mfma_f32_32x32x16_bf16 v[64:79], v[178:181], v[102:105], v[64:79]
	ds_read_b128 v[174:177], v141 offset:32768
	ds_read_b128 v[178:181], v141 offset:40960
	s_waitcnt lgkmcnt(1)
	v_mfma_f32_32x32x16_bf16 v[80:95], v[174:177], v[98:101], v[80:95]
	v_exp_f32_e32 v174, v167
	v_exp_f32_e32 v175, v168
	v_exp_f32_e32 v176, v169
	v_exp_f32_e32 v177, v170
	v_add_f32_e32 v139, v174, v139
	v_add_f32_e32 v139, v175, v139
	v_add_f32_e32 v139, v176, v139
	s_waitcnt lgkmcnt(0)
	v_mfma_f32_32x32x16_bf16 v[64:79], v[178:181], v[98:101], v[64:79]
	v_exp_f32_e32 v178, v171
	v_exp_f32_e32 v179, v144
	v_exp_f32_e32 v180, v146
	v_add_f32_e32 v139, v177, v139
	v_exp_f32_e32 v181, v147
	v_add_f32_e32 v139, v178, v139
	v_add_f32_e32 v139, v179, v139
	v_add_f32_e32 v139, v145, v139
	v_add_f32_e32 v139, v180, v139
	v_add_f32_e32 v139, v181, v139
	v_add_f32_e32 v139, v182, v139
	v_add_f32_e32 v139, v183, v139
	v_add_f32_e32 v139, v184, v139
	v_add_f32_e32 v139, v185, v139
	v_add_f32_e32 v139, v186, v139
	v_add_f32_e32 v139, v187, v139
	v_add_f32_e32 v139, v137, v139
	v_mov_b32_e32 v144, v139
	s_nop 1
	v_permlane32_swap_b32_e32 v139, v144
	v_cvt_pk_bf16_f32 v146, v127, v129
	v_cvt_pk_bf16_f32 v147, v125, v128
	v_cvt_pk_bf16_f32 v148, v123, v126
	v_cvt_pk_bf16_f32 v149, v122, v124
	v_cvt_pk_bf16_f32 v166, v119, v121
	v_cvt_pk_bf16_f32 v167, v117, v120
	v_cvt_pk_bf16_f32 v168, v115, v118
	v_cvt_pk_bf16_f32 v169, v114, v116
	v_cvt_pk_bf16_f32 v170, v174, v175
	v_cvt_pk_bf16_f32 v171, v176, v177
	v_cvt_pk_bf16_f32 v172, v178, v179
	v_cvt_pk_bf16_f32 v173, v145, v180
	v_cvt_pk_bf16_f32 v174, v181, v182
	v_cvt_pk_bf16_f32 v175, v183, v184
	v_cvt_pk_bf16_f32 v176, v185, v186
	v_cvt_pk_bf16_f32 v177, v187, v137
	s_nop 0
	v_permlane32_swap_b32_e32 v146, v148
	v_permlane32_swap_b32_e32 v147, v149
	v_permlane32_swap_b32_e32 v166, v168
	v_permlane32_swap_b32_e32 v167, v169
	v_permlane32_swap_b32_e32 v170, v172
	v_permlane32_swap_b32_e32 v171, v173
	v_permlane32_swap_b32_e32 v174, v176
	v_permlane32_swap_b32_e32 v175, v177
	v_add_u32_e32 v118, 0x20000, v96
	v_add_u32_e32 v122, 0x30000, v96
	global_load_dwordx4 v[114:117], v118, s[58:59]
	s_nop 0
	global_load_dwordx4 v[118:121], v118, s[28:29]
	s_nop 0
	global_load_dwordx4 v[126:129], v122, s[58:59]
	s_nop 0
	global_load_dwordx4 v[122:125], v122, s[28:29]
	ds_read_b64_tr_b16 v[178:179], v159 offset:0
	ds_read_b64_tr_b16 v[180:181], v159 offset:0x800
	ds_read_b64_tr_b16 v[182:183], v159 offset:0x1000
	ds_read_b64_tr_b16 v[184:185], v159 offset:0x1800
	ds_read_b64_tr_b16 v[186:187], v159 offset:0x2000
	ds_read_b64_tr_b16 v[188:189], v159 offset:0x2800
	ds_read_b64_tr_b16 v[212:213], v159 offset:0x3000
	ds_read_b64_tr_b16 v[214:215], v159 offset:0x3800
	s_waitcnt lgkmcnt(0)
	s_nop 0
	v_mfma_f32_32x32x16_bf16 v[48:63], v[146:149], v[178:181], v[48:63]
	ds_read_b64_tr_b16 v[178:179], v159 offset:0x200
	ds_read_b64_tr_b16 v[180:181], v159 offset:0xa00
	v_max_f32_e32 v255, v81, v81
	v_max_f32_e32 v210, v80, v80
	v_max_f32_e32 v255, v210, v255
	v_max3_f32 v255, v255, v82, v83
	v_max3_f32 v255, v255, v84, v85
	v_mfma_f32_32x32x16_bf16 v[48:63], v[166:169], v[182:185], v[48:63]
	ds_read_b64_tr_b16 v[182:183], v159 offset:0x1200
	ds_read_b64_tr_b16 v[184:185], v159 offset:0x1a00
	v_max3_f32 v255, v255, v86, v87
	v_max3_f32 v255, v255, v88, v89
	v_max3_f32 v255, v255, v90, v91
	v_max3_f32 v255, v255, v92, v93
	v_max3_f32 v255, v255, v94, v95
	v_mfma_f32_32x32x16_bf16 v[48:63], v[170:173], v[186:189], v[48:63]
	ds_read_b64_tr_b16 v[186:187], v159 offset:0x2200
	ds_read_b64_tr_b16 v[188:189], v159 offset:0x2a00
	v_max3_f32 v255, v255, v64, v65
	v_max3_f32 v255, v255, v66, v67
	v_max3_f32 v255, v255, v68, v69
	v_max3_f32 v255, v255, v70, v71
	v_max3_f32 v255, v255, v72, v73
	v_mfma_f32_32x32x16_bf16 v[48:63], v[174:177], v[212:215], v[48:63]
	ds_read_b64_tr_b16 v[212:213], v159 offset:0x3200
	ds_read_b64_tr_b16 v[214:215], v159 offset:0x3a00
	v_max3_f32 v255, v255, v74, v75
	v_max3_f32 v255, v255, v76, v77
	v_max3_f32 v255, v255, v78, v79
	v_mov_b32_e32 v210, v255
	s_nop 1
	v_permlane32_swap_b32_e32 v255, v210
	s_waitcnt lgkmcnt(0)
; #define SBAR() __builtin_amdgcn_sched_barrier(0)
; #define SWAIT() asm volatile("s_waitcnt vmcnt(0)" ::: "memory")
; __device__ __forceinline__ void partialSM(f32x16& p0, f32x16& p1, float& m_reg, float& mn, float& alpha) {
;     ...
;     if (__builtin_expect(__all(pmax - m_reg <= THR / SCALE), 1)) { mn = m_reg; alpha = 1.f; }
;     else { mn = fmaxf(m_reg, pmax); alpha = __builtin_amdgcn_exp2f((m_reg - mn) * C); m_reg = mn; }
;     const float mnC = -mn * C;
; #pragma unroll
;     for (int r = 0; r < 16; ++r) p0[r] = fmaf(p0[r], C, mnC);
; #pragma unroll
;     for (int r = 0; r < 16; ++r) p1[r] = fmaf(p1[r], C, mnC);
; #pragma unroll
;     for (int r = 0; r < 16; ++r) p0[r] = __builtin_amdgcn_exp2f(p0[r]);
; __device__ __forceinline__ void attn_unit(const bf16_t* Qb, const bf16_t* Kh, const bf16_t* Vh, bf16_t* Ob, float* scr, int seq, float lam, float onemli, const float* subg, char* lds) {
;     ...
;         f32x16 pA0, pA1, pB0, pB1; float mnA, mnB, alA, alB; bf16x8 pa0, pa1, pa2, pa3;
;         constexpr int SE = 0, SO = 0;
;         __syncthreads();
;         SLOAD(SE, 0); asm volatile("s_waitcnt vmcnt(0)" ::: "memory"); SWRITE(0, SE); __syncthreads();
;         qkt(pA0, pA1, K_lds, qr, r32, hi, comp); partialSM(pA0, pA1, m_reg, mnA, alA);
;         SLOAD(SO, KVBLK);
;         SWAIT(); SWRITE(1, SO); __syncthreads();
;         for (int j = 1; j + 1 < NT; j += 2) {
;             SBAR(); qkt(pB0, pB1, K_lds + SHM_K, qr, r32, hi, comp);
;             finishSM(pA0, pA1, alA, l_reg, pa0, pa1, pa2, pa3); SBAR();
;             SLOAD(SO, (j + 1) * KVBLK); SBAR();
;             pv_d0(o, vb0, pa0, pa1, pa2, pa3); partialSM(pB0, pB1, m_reg, mnB, alB);
;             __syncthreads(); SWAIT(); SWRITE(0, SE);
;             RESC(alB); __syncthreads();
;             SBAR(); qkt(pA0, pA1, K_lds, qr, r32, hi, comp);
;             finishSM(pB0, pB1, alB, l_reg, pa0, pa1, pa2, pa3); SBAR();
;             SLOAD(SE, (j + 2) * KVBLK); SBAR();
;             pv_d0(o, vb0 + (int)SHM_V, pa0, pa1, pa2, pa3); partialSM(pA0, pA1, m_reg, mnA, alA);
;             __syncthreads(); SWAIT(); SWRITE(1, SO);
;             RESC(alA); __syncthreads();
	v_mfma_f32_32x32x16_bf16 v[32:47], v[146:149], v[178:181], v[32:47]
	ds_read_b64_tr_b16 v[178:179], v159 offset:0x400
	ds_read_b64_tr_b16 v[180:181], v159 offset:0xc00
	v_max_f32_e32 v210, v210, v210
	v_max_f32_e32 v255, v255, v255
	v_max_f32_e32 v255, v255, v210
	v_sub_f32_e32 v210, v255, v134
	v_cmp_ge_f32_e32 vcc, s65, v210
	v_mfma_f32_32x32x16_bf16 v[32:47], v[166:169], v[182:185], v[32:47]
	ds_read_b64_tr_b16 v[182:183], v159 offset:0x1400
	ds_read_b64_tr_b16 v[184:185], v159 offset:0x1c00
	v_max_f32_e32 v210, v134, v134
	v_max_f32_e32 v210, v210, v255
	v_sub_f32_e32 v255, v134, v210
	v_mul_f32_e32 v255, 0x3e38aa3b, v255
	v_exp_f32_e32 v255, v255
	v_mfma_f32_32x32x16_bf16 v[32:47], v[170:173], v[186:189], v[32:47]
	ds_read_b64_tr_b16 v[186:187], v159 offset:0x2400
	ds_read_b64_tr_b16 v[188:189], v159 offset:0x2c00
	s_cmp_eq_u64 vcc, exec
	s_cselect_b64 s[8:9], -1, 0
	v_cndmask_b32_e64 v255, v255, 1.0, s[8:9]
	v_cndmask_b32_e64 v134, v210, v134, s[8:9]
	v_mul_f32_e32 v210, 0xbe38aa3b, v134
	v_mfma_f32_32x32x16_bf16 v[32:47], v[174:177], v[212:215], v[32:47]
	ds_read_b64_tr_b16 v[212:213], v159 offset:0x3400
	ds_read_b64_tr_b16 v[214:215], v159 offset:0x3c00
	v_pk_fma_f32 v[80:81], v[80:81], s[72:73], v[210:211] op_sel_hi:[1,0,0]
	v_pk_fma_f32 v[82:83], v[82:83], s[72:73], v[210:211] op_sel_hi:[1,0,0]
	v_pk_fma_f32 v[84:85], v[84:85], s[72:73], v[210:211] op_sel_hi:[1,0,0]
	v_pk_fma_f32 v[86:87], v[86:87], s[72:73], v[210:211] op_sel_hi:[1,0,0]
	v_pk_fma_f32 v[88:89], v[88:89], s[72:73], v[210:211] op_sel_hi:[1,0,0]
	s_waitcnt lgkmcnt(0)
	v_mfma_f32_32x32x16_bf16 v[16:31], v[146:149], v[178:181], v[16:31]
	ds_read_b64_tr_b16 v[178:179], v159 offset:0x600
	ds_read_b64_tr_b16 v[180:181], v159 offset:0xe00
	v_pk_fma_f32 v[90:91], v[90:91], s[72:73], v[210:211] op_sel_hi:[1,0,0]
	v_pk_fma_f32 v[92:93], v[92:93], s[72:73], v[210:211] op_sel_hi:[1,0,0]
	v_pk_fma_f32 v[94:95], v[94:95], s[72:73], v[210:211] op_sel_hi:[1,0,0]
	v_exp_f32_e32 v240, v80
	v_mfma_f32_32x32x16_bf16 v[16:31], v[166:169], v[182:185], v[16:31]
	ds_read_b64_tr_b16 v[182:183], v159 offset:0x1600
	ds_read_b64_tr_b16 v[184:185], v159 offset:0x1e00
	v_exp_f32_e32 v241, v81
	v_exp_f32_e32 v242, v82
	v_exp_f32_e32 v243, v83
	v_mfma_f32_32x32x16_bf16 v[16:31], v[170:173], v[186:189], v[16:31]
	ds_read_b64_tr_b16 v[186:187], v159 offset:0x2600
	ds_read_b64_tr_b16 v[188:189], v159 offset:0x2e00
	v_exp_f32_e32 v244, v84
	v_exp_f32_e32 v245, v85
	v_exp_f32_e32 v246, v86
	v_mfma_f32_32x32x16_bf16 v[16:31], v[174:177], v[212:215], v[16:31]
	ds_read_b64_tr_b16 v[212:213], v159 offset:0x3600
	ds_read_b64_tr_b16 v[214:215], v159 offset:0x3e00
	v_exp_f32_e32 v247, v87
	v_exp_f32_e32 v248, v88
	v_exp_f32_e32 v249, v89
	s_waitcnt lgkmcnt(0)
	v_mfma_f32_32x32x16_bf16 v[0:15], v[146:149], v[178:181], v[0:15]
	s_barrier
	s_waitcnt vmcnt(0)
	s_waitcnt vmcnt(3)
	ds_write_b128 v163, v[114:117] offset:16384
	s_waitcnt vmcnt(1)
	ds_write_b128 v164, v[126:129] offset:16384
	ds_write_b128 v161, v[118:121] offset:49152
	s_waitcnt vmcnt(0)
	ds_write_b128 v162, v[122:125] offset:49152
	v_exp_f32_e32 v250, v90
	v_exp_f32_e32 v251, v91
	v_exp_f32_e32 v206, v92
	v_mfma_f32_32x32x16_bf16 v[0:15], v[166:169], v[182:185], v[0:15]
	v_exp_f32_e32 v207, v93
	v_exp_f32_e32 v208, v94
	v_exp_f32_e32 v209, v95
	v_mfma_f32_32x32x16_bf16 v[0:15], v[170:173], v[186:189], v[0:15]
	v_mfma_f32_32x32x16_bf16 v[0:15], v[174:177], v[212:215], v[0:15]
	v_mov_b32_e32 v137, v255
	v_cmp_gt_f32_e32 vcc, 1.0, v137
	s_cbranch_vccz .LBB0_288
	s_and_saveexec_b64 s[2:3], s[6:7]
	ds_write_b32 v157, v137 offset:128
	s_or_b64 exec, exec, s[2:3]
	s_waitcnt lgkmcnt(0)
	ds_read_b128 v[114:117], v158 offset:224
	ds_read_b128 v[118:121], v158 offset:192
	ds_read_b128 v[122:125], v158 offset:160
	ds_read_b128 v[126:129], v158 offset:128
	s_waitcnt lgkmcnt(3)
	v_pk_mul_f32 v[62:63], v[62:63], v[116:117]
	s_waitcnt lgkmcnt(2)
	v_pk_mul_f32 v[58:59], v[58:59], v[120:121]
	s_waitcnt lgkmcnt(1)
	v_pk_mul_f32 v[54:55], v[54:55], v[124:125]
	s_waitcnt lgkmcnt(0)
	v_pk_mul_f32 v[50:51], v[50:51], v[128:129]
	v_pk_mul_f32 v[60:61], v[60:61], v[114:115]
	v_pk_mul_f32 v[56:57], v[56:57], v[118:119]
	v_pk_mul_f32 v[52:53], v[52:53], v[122:123]
	v_pk_mul_f32 v[48:49], v[48:49], v[126:127]
	v_pk_mul_f32 v[46:47], v[46:47], v[116:117]
	v_pk_mul_f32 v[42:43], v[42:43], v[120:121]
	v_pk_mul_f32 v[38:39], v[38:39], v[124:125]
	v_pk_mul_f32 v[34:35], v[34:35], v[128:129]
	v_pk_mul_f32 v[44:45], v[44:45], v[114:115]
	v_pk_mul_f32 v[40:41], v[40:41], v[118:119]
	v_pk_mul_f32 v[36:37], v[36:37], v[122:123]
	v_pk_mul_f32 v[32:33], v[32:33], v[126:127]
	v_pk_mul_f32 v[30:31], v[30:31], v[116:117]
	v_pk_mul_f32 v[26:27], v[26:27], v[120:121]
	v_pk_mul_f32 v[22:23], v[22:23], v[124:125]
	v_pk_mul_f32 v[18:19], v[18:19], v[128:129]
	v_pk_mul_f32 v[28:29], v[28:29], v[114:115]
	v_pk_mul_f32 v[24:25], v[24:25], v[118:119]
	v_pk_mul_f32 v[20:21], v[20:21], v[122:123]
	v_pk_mul_f32 v[16:17], v[16:17], v[126:127]
	v_pk_mul_f32 v[14:15], v[14:15], v[116:117]
	v_pk_mul_f32 v[10:11], v[10:11], v[120:121]
	v_pk_mul_f32 v[6:7], v[6:7], v[124:125]
	v_pk_mul_f32 v[2:3], v[2:3], v[128:129]
	v_pk_mul_f32 v[12:13], v[12:13], v[114:115]
	v_pk_mul_f32 v[8:9], v[8:9], v[118:119]
	v_pk_mul_f32 v[4:5], v[4:5], v[122:123]
	v_pk_mul_f32 v[0:1], v[0:1], v[126:127]
